# attention tile loops: waves 4-7 run rescale+PV one tile late (after the next barrier) to overlap partner wave softmax; all 4 loops
# speedup vs baseline: 1.0078x; 1.0078x over previous
; #define LAS __attribute__((address_space(3)))
; #define IN(k) (lo <= (k) && (k) < hi && phase_begin(F))
; #define SEAM(k) do { if (lo <= (k) && (k) + 1 < hi) xcd_barrier(bar); } while (0)
; template <class CM>
; __device__ __forceinline__ void p0_transpose_matrix(Frame& F, const float* W, int K, int N, bf16* WT, int nblk, CM colmap, int& it0, const float* kgain = nullptr) {
;     float* scr = (float*)(F.lds + RING_OFF + F.wave * 16384);
;     const int nitems = (K / 64) * nblk;
;     int first = (F.gw - (it0 % F.ngw) + F.ngw) % F.ngw;
;     for (int r = first; r < nitems; r += F.ngw) {
;         const int kb = r / nblk, nb = r % nblk;
;         p0_transpose_item(W, K, N, WT, kb, colmap(nb), nb * 32, scr, F.lane, kgain);
; __global__ void __launch_bounds__(NTHREADS, 2) fwd_kernel(Args args) {
;     ...
;     F.tid = threadIdx.x; F.lane = F.tid & 63; F.wave = __builtin_amdgcn_readfirstlane(F.tid >> 6);
;     F.G = gridDim.x; { const int bx = blockIdx.x; F.vcu = (F.G % 8 == 0) ? (bx % 8) * (F.G / 8) + bx / 8 : bx; }
;     F.gw = F.vcu * NWAVES + F.wave; F.ngw = F.G * NWAVES;
;     F.kin = (const float* const __attribute__((address_space(4)))*)__builtin_amdgcn_kernarg_segment_ptr();
;     F.out = args.out; F.ws = args.ws;
;     volatile LAS unsigned* MISC = (volatile LAS unsigned*)((LAS unsigned char*)lds + MISC_OFF);
;     if (F.tid < 32) MISC[F.tid] = 0u;
;     __syncthreads();
;     const int lo = args.ph_lo, hi = args.ph_hi;
;     unsigned* barw = (unsigned*)(F.ws + WS_CTL) + CW_BAR + args.li * XCD_BAR_WORDS;
;     XcdBarrier bar; bar.bar = barw; bar.x = 0; bar.st = nullptr;
;     if (hi - lo > 1) bar = xcd_barrier_post(barw, MISC + 8);
;     ...
;     const bool p_split = (F.G == 256) && (lo <= 0 && 1 < hi);
;     if (IN(0)) { p0_prologue(F, p_split); } SEAM(0);
.LBB0_8:
	s_lshr_b32 s90, s86, 6
	s_cmp_gt_u32 s90, 3
	s_cselect_b32 s100, 1, 0
	s_mov_b32 s99, 0
	s_lshl_b32 s0, s87, 3
	v_writelane_b32 v254, s6, 7
	s_add_i32 s0, s0, s90
	s_lshl_b32 s76, s83, 3
	v_writelane_b32 v254, s7, 8
	s_cmpk_eq_i32 s83, 0x100
	v_writelane_b32 v254, s0, 9
	s_cselect_b64 s[10:11], -1, 0
	s_cmpk_lg_i32 s83, 0x100
	v_writelane_b32 v254, s1, 10
	s_cselect_b64 s[0:1], -1, 0
	v_writelane_b32 v254, s0, 11
	v_mov_b32_e32 v216, v0
	s_nop 0
	v_writelane_b32 v254, s1, 12
	s_nop 0
	v_readlane_b32 s0, v254, 0
	v_readlane_b32 s1, v254, 1
	s_mov_b64 s[4:5], s[0:1]
	s_cmp_lt_i32 s4, 1
	s_cselect_b64 s[6:7], -1, 0
	s_cmp_gt_i32 s5, 1
	v_readlane_b32 s2, v254, 2
	v_readlane_b32 s3, v254, 3
	s_cselect_b64 s[8:9], -1, 0
	v_writelane_b32 v254, s10, 13
	s_and_b64 s[0:1], s[10:11], s[6:7]
	s_and_b64 s[0:1], s[0:1], s[8:9]
	s_xor_b64 s[0:1], s[0:1], -1
	s_cmp_gt_i32 s5, 0
	s_cselect_b64 s[2:3], -1, 0
	s_and_b64 s[2:3], s[6:7], s[2:3]
	s_andn2_b64 vcc, exec, s[2:3]
	v_writelane_b32 v254, s11, 14
	s_cbranch_vccnz .LBB0_149
	v_readlane_b32 s2, v254, 7
	v_mov_b32_e32 v216, v0
	v_readlane_b32 s3, v254, 8
	s_andn2_b64 vcc, exec, s[0:1]
	v_writelane_b32 v254, s2, 7
	v_and_b32_e32 v18, 63, v216
	s_nop 0
	v_writelane_b32 v254, s3, 8
	s_cbranch_vccnz .LBB0_135
	s_abs_i32 s16, s76
	v_cvt_f32_u32_e32 v1, s16
	s_sub_i32 s10, 0, s16
	v_readlane_b32 s2, v254, 7
	v_readlane_b32 s12, v254, 9
	v_rcp_iflag_f32_e32 v1, v1
	v_readlane_b32 s3, v254, 8
	s_add_i32 s17, s12, s76
	s_load_dwordx2 s[4:5], s[2:3], 0x8
	v_mul_f32_e32 v1, 0x4f7ffffe, v1
	v_cvt_u32_f32_e32 v1, v1
	s_abs_i32 s3, s17
	s_lshl_b32 s2, s90, 14
	s_add_i32 s19, s2, 0
	v_readfirstlane_b32 s18, v1
	s_mul_i32 s10, s10, s18
	s_mul_hi_u32 s10, s18, s10
	s_add_i32 s18, s18, s10
	s_mul_hi_u32 s10, s3, s18
	s_mul_i32 s10, s10, s16
	s_sub_i32 s3, s3, s10
	s_ashr_i32 s2, s17, 31
	s_sub_i32 s10, s3, s16
	s_cmp_ge_u32 s3, s16
	s_cselect_b32 s3, s10, s3
	s_sub_i32 s10, s3, s16
	s_cmp_ge_u32 s3, s16
	s_cselect_b32 s3, s10, s3
	s_xor_b32 s3, s3, s2
	s_sub_i32 s20, s3, s2
	s_mov_b32 s11, 0
	v_and_b32_e32 v32, 7, v216
	s_cmpk_gt_i32 s20, 0x59ff
	v_lshrrev_b32_e32 v19, 5, v18
	v_lshlrev_b32_e32 v33, 2, v216
	v_lshrrev_b32_e32 v1, 3, v18
	v_readlane_b32 s13, v254, 10
	s_cbranch_scc1 .LBB0_33
	v_readlane_b32 s2, v254, 7
	v_readlane_b32 s3, v254, 8
	s_load_dwordx2 s[2:3], s[2:3], 0x18
	v_lshlrev_b32_e32 v2, 5, v32
	v_mov_b32_e32 v3, 0
	v_lshrrev_b32_e32 v34, 5, v18
	s_waitcnt lgkmcnt(0)
	v_lshl_add_u64 v[20:21], s[4:5], 0, v[2:3]
	v_and_b32_e32 v2, 0x7c, v33
	v_mul_u32_u24_e32 v4, 0x84, v34
	s_cmp_lg_u64 s[4:5], 0
	v_lshl_add_u64 v[22:23], s[2:3], 0, v[2:3]
	v_add3_u32 v35, s19, v4, v2
	v_lshrrev_b32_e32 v36, 3, v18
	v_lshlrev_b32_e32 v2, 4, v32
	s_cselect_b64 s[12:13], -1, 0
	v_mul_u32_u24_e32 v6, 0x420, v32
	v_lshl_add_u64 v[4:5], s[70:71], 0, v[2:3]
	v_lshlrev_b32_e32 v2, 2, v36
	s_mov_b64 s[2:3], 0x200000
	v_add3_u32 v37, s19, v6, v2
	v_cndmask_b32_e64 v2, 0, 1, s[12:13]
	v_lshl_add_u64 v[24:25], v[4:5], 0, s[2:3]
	s_lshl_b32 s21, s20, 5
	s_lshl_b32 s22, s76, 5
	v_cmp_ne_u32_e64 s[2:3], 1, v2
	s_mov_b32 s23, 0xb180
	v_add_u32_e32 v38, 0x400, v35
	v_add_u32_e32 v39, 0x800, v35
	v_add_u32_e32 v40, 0xc00, v35
	v_add_u32_e32 v41, 0x1000, v35
	v_add_u32_e32 v42, 0x1400, v35
	v_add_u32_e32 v43, 0x1800, v35
	v_add_u32_e32 v44, 0x1c00, v35
	v_mov_b32_e32 v2, v3
	v_mov_b32_e32 v4, v3
	v_mov_b32_e32 v5, v3
	s_branch .LBB0_13

; #define TWAIT() do { asm volatile("s_waitcnt vmcnt(0)" ::: "memory"); __syncthreads(); } while (0)
; template <int VAR>
; __device__ __forceinline__ void nsa_attn_mfma(Frame& F, bf16* Y) {
;     ...
;       if (VAR < 5) for (;;) {
;         const int kbuf = it & 1;
;         TWAIT();
;         const int kbn = tiles ? 31 - __builtin_clz(tiles) : -1; const int vbn = (vbuf == 2) ? 0 : vbuf + 1;
;         if (kbn >= 0) { tiles &= ~(1u << kbn); TDMA(kgp + (size_t)kbn * 64 * NSA_NP, vgp + (size_t)kbn * 64 * NSA_NP, NSA_NP, kbuf ^ 1, vbn); }
;         else if (br == 0) TDMA(kgp + (size_t)cur * 64 * NSA_NP + (NSA_KW - NSA_KS), vgp + (size_t)cur * 64 * NSA_NP + (NSA_VW - NSA_VS), NSA_NP, kbuf ^ 1, vbn);
.LBB0_866:
	s_add_i32 s94, s94, 1
	s_and_b32 s10, s94, 1
	s_cmp_eq_u32 s7, 0
	s_waitcnt vmcnt(0)
	s_cselect_b64 s[0:1], -1, 0
	s_add_i32 s4, s95, 1
	s_cmp_lg_u32 s95, 2
	s_cselect_b32 s91, s4, 0
	s_and_b64 vcc, exec, s[0:1]
	s_waitcnt lgkmcnt(0)
	s_barrier
	s_cmp_eq_u32 s99, 1
	s_cbranch_scc1 .Lmy_pv_s0
.Lmy_ret_s0:
	s_and_b64 vcc, exec, s[0:1]
	s_cbranch_vccz .LBB0_868
	s_lshl_b32 s8, s10, 14
	s_xor_b32 s4, s8, 0x4000
	s_add_i32 s4, s83, s4
	s_lshl_b32 s9, s91, 14
	s_add_i32 s5, s83, s9
	s_mov_b32 m0, s4
	s_add_i32 s5, s5, 0x8000
	global_load_lds_dwordx4 v[156:157], off
	s_add_i32 m0, s4, 0x2000
	s_nop 0
	global_load_lds_dwordx4 v[158:159], off
	s_mov_b32 m0, s5
	s_mov_b64 s[4:5], 0
	global_load_lds_dwordx4 v[160:161], off
	s_branch .LBB0_869

; __device__ __forceinline__ float swapmax(float x) { auto rr = __builtin_amdgcn_permlane32_swap(__float_as_uint(x), __float_as_uint(x), false, false); return fmaxf(__uint_as_float(rr[0]), __uint_as_float(rr[1])); }
; __device__ __forceinline__ float swapsum(float x) { auto rr = __builtin_amdgcn_permlane32_swap(__float_as_uint(x), __float_as_uint(x), false, false); return __uint_as_float(rr[0]) + __uint_as_float(rr[1]); }
; __device__ __forceinline__ void softmax_step(f32x16& p0, f32x16& p1, float& m, float& l, float& alpha, bf16x8& pa0, bf16x8& pa1, bf16x8& pa2, bf16x8& pa3) {
;   float pmax = p0[0];
; #pragma unroll
;   for (int r = 1; r < 16; ++r) pmax = fmaxf(pmax, p0[r]);
; #pragma unroll
;   for (int r = 0; r < 16; ++r) pmax = fmaxf(pmax, p1[r]);
;   pmax = swapmax(pmax);
;   if (__all(pmax - m <= THR2)) { alpha = 1.f; }
;   else { const float mn = fmaxf(m, pmax); alpha = __builtin_amdgcn_exp2f(m - mn); m = mn; }
;   float ps = 0.f;
; #pragma unroll
;   for (int r = 0; r < 16; ++r) { p0[r] = __builtin_amdgcn_exp2f(p0[r] - m); ps += p0[r]; }
; #pragma unroll
;   for (int r = 0; r < 16; ++r) { p1[r] = __builtin_amdgcn_exp2f(p1[r] - m); ps += p1[r]; }
;   ps = swapsum(ps);
;   l = l * alpha + ps;
;   PK4(p0, 0, pa0); PK4(p0, 8, pa1); PK4(p1, 0, pa2); PK4(p1, 8, pa3);
; }
.LBB0_873:
	v_max_f32_e32 v81, v164, v164
	v_max_f32_e32 v82, v2, v2
	v_max_f32_e32 v81, v82, v81
	v_max3_f32 v81, v81, v165, v166
	v_max3_f32 v81, v81, v167, v168
	v_max3_f32 v81, v81, v169, v170
	v_max3_f32 v81, v81, v171, v92
	v_max3_f32 v81, v81, v93, v76
	v_max3_f32 v81, v81, v77, v78
	v_max3_f32 v81, v81, v79, v80
	v_max3_f32 v81, v81, v90, v91
	v_max3_f32 v81, v81, v88, v89
	v_max3_f32 v81, v81, v86, v87
	v_max3_f32 v81, v81, v84, v85
	v_max3_f32 v81, v81, v70, v71
	v_max3_f32 v81, v81, v72, v73
	v_max3_f32 v81, v81, v68, v69
	v_max3_f32 v81, v81, v74, v75
	v_mov_b32_e32 v82, v81
	s_nop 1
	v_permlane32_swap_b32_e32 v81, v82
	v_max_f32_e32 v82, v82, v82
	v_max_f32_e32 v81, v81, v81
	v_max_f32_e32 v81, v81, v82
	v_sub_f32_e32 v82, v81, v197
	v_max_f32_e32 v83, v197, v197
	v_cmp_ge_f32_e32 vcc, s88, v82
	v_max_f32_e32 v81, v83, v81
	s_cmp_eq_u64 vcc, exec
	v_sub_f32_e32 v83, v197, v81
	s_cselect_b64 vcc, -1, 0
	v_exp_f32_e32 v83, v83
	v_cndmask_b32_e32 v197, v81, v197, vcc
	v_sub_f32_e32 v2, v2, v197
	v_exp_f32_e32 v81, v2
	v_sub_f32_e32 v2, v164, v197
	v_exp_f32_e32 v82, v2
	v_sub_f32_e32 v2, v165, v197
	v_cndmask_b32_e64 v94, v83, 1.0, vcc
	v_exp_f32_e32 v83, v2
	v_sub_f32_e32 v2, v166, v197
	v_exp_f32_e32 v95, v2
	v_sub_f32_e32 v96, v167, v197
	v_add_f32_e32 v2, 0, v81
	v_exp_f32_e32 v96, v96
	v_sub_f32_e32 v97, v168, v197
	v_add_f32_e32 v2, v82, v2
	v_exp_f32_e32 v97, v97
	v_sub_f32_e32 v98, v169, v197
	v_add_f32_e32 v2, v83, v2
	v_exp_f32_e32 v98, v98
	v_sub_f32_e32 v99, v170, v197
	v_add_f32_e32 v2, v95, v2
	v_exp_f32_e32 v99, v99
	v_sub_f32_e32 v164, v171, v197
	v_add_f32_e32 v2, v96, v2
	v_exp_f32_e32 v164, v164
	v_sub_f32_e32 v92, v92, v197
	v_add_f32_e32 v2, v97, v2
	v_exp_f32_e32 v92, v92
	v_sub_f32_e32 v93, v93, v197
	v_add_f32_e32 v2, v98, v2
	v_exp_f32_e32 v93, v93
	v_sub_f32_e32 v76, v76, v197
	v_add_f32_e32 v2, v99, v2
	v_exp_f32_e32 v76, v76
	v_sub_f32_e32 v77, v77, v197
	v_add_f32_e32 v2, v164, v2
	v_exp_f32_e32 v77, v77
	v_sub_f32_e32 v78, v78, v197
	v_add_f32_e32 v2, v92, v2
	v_exp_f32_e32 v78, v78
	v_sub_f32_e32 v79, v79, v197
	v_add_f32_e32 v2, v93, v2
	v_exp_f32_e32 v79, v79
	v_sub_f32_e32 v80, v80, v197
	v_add_f32_e32 v2, v76, v2
	v_exp_f32_e32 v80, v80
	v_sub_f32_e32 v90, v90, v197
	v_add_f32_e32 v2, v77, v2
	v_exp_f32_e32 v90, v90
	v_sub_f32_e32 v91, v91, v197
	v_add_f32_e32 v2, v78, v2
	v_exp_f32_e32 v91, v91
	v_sub_f32_e32 v88, v88, v197
	v_add_f32_e32 v2, v79, v2
	v_exp_f32_e32 v88, v88
	v_sub_f32_e32 v89, v89, v197
	v_add_f32_e32 v2, v80, v2
	v_exp_f32_e32 v89, v89
	v_sub_f32_e32 v86, v86, v197
	v_add_f32_e32 v2, v90, v2
	v_exp_f32_e32 v86, v86
	v_sub_f32_e32 v87, v87, v197
	v_add_f32_e32 v2, v91, v2
	v_exp_f32_e32 v87, v87
	v_sub_f32_e32 v84, v84, v197
	v_add_f32_e32 v2, v88, v2
	v_exp_f32_e32 v165, v84
	v_sub_f32_e32 v84, v85, v197
	v_add_f32_e32 v2, v89, v2
	v_exp_f32_e32 v85, v84
	v_sub_f32_e32 v70, v70, v197
	v_add_f32_e32 v2, v86, v2
	v_exp_f32_e32 v166, v70
	v_sub_f32_e32 v70, v71, v197
	v_add_f32_e32 v2, v87, v2
	v_exp_f32_e32 v167, v70
	v_sub_f32_e32 v70, v72, v197
	v_add_f32_e32 v2, v165, v2
	v_exp_f32_e32 v168, v70
	v_sub_f32_e32 v70, v73, v197
	v_add_f32_e32 v2, v85, v2
	v_exp_f32_e32 v169, v70
	v_sub_f32_e32 v68, v68, v197
	v_add_f32_e32 v2, v166, v2
	v_exp_f32_e32 v170, v68
	v_sub_f32_e32 v68, v69, v197
	v_add_f32_e32 v2, v167, v2
	v_exp_f32_e32 v171, v68
	v_sub_f32_e32 v68, v74, v197
	v_add_f32_e32 v2, v168, v2
	v_exp_f32_e32 v199, v68
	v_sub_f32_e32 v68, v75, v197
	v_add_f32_e32 v2, v169, v2
	v_exp_f32_e32 v200, v68
	v_add_f32_e32 v2, v170, v2
	v_add_f32_e32 v2, v171, v2
	v_add_f32_e32 v2, v199, v2
	v_add_f32_e32 v2, v200, v2
	v_mov_b32_e32 v84, v2
	v_cvt_pk_bf16_f32 v68, v81, v82
	v_cvt_pk_bf16_f32 v69, v83, v95
	v_cvt_pk_bf16_f32 v70, v96, v97
	v_cvt_pk_bf16_f32 v71, v98, v99
	v_cvt_pk_bf16_f32 v72, v164, v92
	v_cvt_pk_bf16_f32 v73, v93, v76
	v_cvt_pk_bf16_f32 v74, v77, v78
	v_cvt_pk_bf16_f32 v75, v79, v80
	v_cvt_pk_bf16_f32 v80, v90, v91
	v_cvt_pk_bf16_f32 v81, v88, v89
	v_cvt_pk_bf16_f32 v82, v86, v87
	v_cvt_pk_bf16_f32 v83, v165, v85
	v_cvt_pk_bf16_f32 v76, v166, v167
	v_cvt_pk_bf16_f32 v77, v168, v169
	v_cvt_pk_bf16_f32 v78, v170, v171
	v_cvt_pk_bf16_f32 v79, v199, v200
	s_nop 1
	v_permlane32_swap_b32_e32 v2, v84
	v_permlane32_swap_b32_e32 v68, v70
	v_permlane32_swap_b32_e32 v69, v71
	v_permlane32_swap_b32_e32 v72, v74
	v_permlane32_swap_b32_e32 v73, v75
	v_permlane32_swap_b32_e32 v80, v82
	v_permlane32_swap_b32_e32 v81, v83
	v_permlane32_swap_b32_e32 v76, v78
	v_permlane32_swap_b32_e32 v77, v79
	v_add_f32_e32 v2, v2, v84
	v_fmac_f32_e32 v2, v198, v94
	s_cmp_eq_u32 s100, 0
	s_cbranch_scc0 .Lmy_defer_s0
	s_mov_b32 s98, s95
; #define SBAR() __builtin_amdgcn_sched_barrier(0)
; #define PV_RD(D0, L0, H0, L1, H1, L2, H2, L3, H3) do { L0 = tr_read<v_rd_off(D0, 0, 0)>(vb); H0 = tr_read<v_rd_off(D0, 0, 1)>(vb); L1 = tr_read<v_rd_off(D0, 1, 0)>(vb); H1 = tr_read<v_rd_off(D0, 1, 1)>(vb); \
;     L2 = tr_read<v_rd_off(D0, 2, 0)>(vb); H2 = tr_read<v_rd_off(D0, 2, 1)>(vb); L3 = tr_read<v_rd_off(D0, 3, 0)>(vb); H3 = tr_read<v_rd_off(D0, 3, 1)>(vb); } while (0)
; #define PV_MM(OD, L0, H0, L1, H1, L2, H2, L3, H3) do { OD = __builtin_amdgcn_mfma_f32_32x32x16_bf16(pa0, PV_PK(L0, H0), OD, 0, 0, 0); OD = __builtin_amdgcn_mfma_f32_32x32x16_bf16(pa1, PV_PK(L1, H1), OD, 0, 0, 0); \
;     OD = __builtin_amdgcn_mfma_f32_32x32x16_bf16(pa2, PV_PK(L2, H2), OD, 0, 0, 0); OD = __builtin_amdgcn_mfma_f32_32x32x16_bf16(pa3, PV_PK(L3, H3), OD, 0, 0, 0); } while (0)
; __device__ __forceinline__ void pv_d0(f32x16* o, int vb, bf16x8 pa0, bf16x8 pa1, bf16x8 pa2, bf16x8 pa3) {
;   s16x4 al0, ah0, al1, ah1, al2, ah2, al3, ah3, bl0, bh0, bl1, bh1, bl2, bh2, bl3, bh3;
;   PV_RD(0, al0, ah0, al1, ah1, al2, ah2, al3, ah3);
;   PV_RD(1, bl0, bh0, bl1, bh1, bl2, bh2, bl3, bh3);
;   asm volatile("s_waitcnt lgkmcnt(8)" ::: "memory"); SBAR();
;   PV_MM(o[0], al0, ah0, al1, ah1, al2, ah2, al3, ah3); SBAR();
;   PV_RD(2, al0, ah0, al1, ah1, al2, ah2, al3, ah3);
;   asm volatile("s_waitcnt lgkmcnt(8)" ::: "memory"); SBAR();
;   PV_MM(o[1], bl0, bh0, bl1, bh1, bl2, bh2, bl3, bh3); SBAR();
;   PV_RD(3, bl0, bh0, bl1, bh1, bl2, bh2, bl3, bh3);
;   asm volatile("s_waitcnt lgkmcnt(8)" ::: "memory"); SBAR();
;   PV_MM(o[2], al0, ah0, al1, ah1, al2, ah2, al3, ah3); SBAR();
;   asm volatile("s_waitcnt lgkmcnt(0)" ::: "memory"); SBAR();
;   PV_MM(o[3], bl0, bh0, bl1, bh1, bl2, bh2, bl3, bh3);
; }
.Lmy_pv_s0:
	v_cmp_gt_f32_e32 vcc, 1.0, v94
	s_cbranch_vccz .LBB0_877
	s_and_saveexec_b64 s[4:5], s[2:3]
	ds_write_b32 v193, v94 offset:128
	s_or_b64 exec, exec, s[4:5]
	s_waitcnt lgkmcnt(0)
	ds_read_b128 v[86:89], v139 offset:224
	ds_read_b128 v[90:93], v139 offset:192
	ds_read_b128 v[96:99], v139 offset:160
	ds_read_b128 v[164:167], v139 offset:128
	s_waitcnt lgkmcnt(0)
	s_waitcnt lgkmcnt(0)
	v_pk_mul_f32 v[66:67], v[66:67], v[88:89]
	v_pk_mul_f32 v[62:63], v[62:63], v[92:93]
	v_pk_mul_f32 v[58:59], v[58:59], v[98:99]
	v_pk_mul_f32 v[54:55], v[54:55], v[166:167]
	v_pk_mul_f32 v[64:65], v[64:65], v[86:87]
	v_pk_mul_f32 v[60:61], v[60:61], v[90:91]
	v_pk_mul_f32 v[56:57], v[56:57], v[96:97]
	v_pk_mul_f32 v[52:53], v[52:53], v[164:165]
	v_pk_mul_f32 v[50:51], v[50:51], v[88:89]
	v_pk_mul_f32 v[46:47], v[46:47], v[92:93]
	v_pk_mul_f32 v[42:43], v[42:43], v[98:99]
	v_pk_mul_f32 v[38:39], v[38:39], v[166:167]
	v_pk_mul_f32 v[48:49], v[48:49], v[86:87]
	v_pk_mul_f32 v[44:45], v[44:45], v[90:91]
	v_pk_mul_f32 v[40:41], v[40:41], v[96:97]
	v_pk_mul_f32 v[36:37], v[36:37], v[164:165]
	v_pk_mul_f32 v[34:35], v[34:35], v[88:89]
	v_pk_mul_f32 v[30:31], v[30:31], v[92:93]
	v_pk_mul_f32 v[26:27], v[26:27], v[98:99]
	v_pk_mul_f32 v[22:23], v[22:23], v[166:167]
	v_pk_mul_f32 v[32:33], v[32:33], v[86:87]
	v_pk_mul_f32 v[28:29], v[28:29], v[90:91]
	v_pk_mul_f32 v[24:25], v[24:25], v[96:97]
	v_pk_mul_f32 v[20:21], v[20:21], v[164:165]
	v_pk_mul_f32 v[18:19], v[18:19], v[88:89]
	v_pk_mul_f32 v[14:15], v[14:15], v[92:93]
	v_pk_mul_f32 v[10:11], v[10:11], v[98:99]
	v_pk_mul_f32 v[6:7], v[6:7], v[166:167]
	v_pk_mul_f32 v[16:17], v[16:17], v[86:87]
	v_pk_mul_f32 v[12:13], v[12:13], v[90:91]
	v_pk_mul_f32 v[8:9], v[8:9], v[96:97]
	v_pk_mul_f32 v[4:5], v[4:5], v[164:165]
.LBB0_877:
	v_lshl_add_u32 v206, s98, 14, v192
	ds_read_b64_tr_b16 v[84:85], v206 offset:0
	ds_read_b64_tr_b16 v[86:87], v206 offset:0x800
	ds_read_b64_tr_b16 v[88:89], v206 offset:0x1000
	ds_read_b64_tr_b16 v[90:91], v206 offset:0x1800
	ds_read_b64_tr_b16 v[92:93], v206 offset:0x2000
	ds_read_b64_tr_b16 v[94:95], v206 offset:0x2800
	ds_read_b64_tr_b16 v[96:97], v206 offset:0x3000
	ds_read_b64_tr_b16 v[98:99], v206 offset:0x3800
	ds_read_b64_tr_b16 v[164:165], v206 offset:0x200
	ds_read_b64_tr_b16 v[166:167], v206 offset:0xa00
	ds_read_b64_tr_b16 v[168:169], v206 offset:0x1200
	ds_read_b64_tr_b16 v[170:171], v206 offset:0x1a00
	ds_read_b64_tr_b16 v[240:241], v206 offset:0x2200
	ds_read_b64_tr_b16 v[242:243], v206 offset:0x2a00
	ds_read_b64_tr_b16 v[244:245], v206 offset:0x3200
	ds_read_b64_tr_b16 v[246:247], v206 offset:0x3a00
	s_waitcnt lgkmcnt(8)
	v_mfma_f32_32x32x16_bf16 v[52:67], v[68:71], v[84:87], v[52:67]
	v_mfma_f32_32x32x16_bf16 v[52:67], v[72:75], v[88:91], v[52:67]
	v_mfma_f32_32x32x16_bf16 v[52:67], v[80:83], v[92:95], v[52:67]
	v_mfma_f32_32x32x16_bf16 v[52:67], v[76:79], v[96:99], v[52:67]
	ds_read_b64_tr_b16 v[84:85], v206 offset:0x400
	ds_read_b64_tr_b16 v[86:87], v206 offset:0xc00
	ds_read_b64_tr_b16 v[88:89], v206 offset:0x1400
	ds_read_b64_tr_b16 v[90:91], v206 offset:0x1c00
	ds_read_b64_tr_b16 v[92:93], v206 offset:0x2400
	ds_read_b64_tr_b16 v[94:95], v206 offset:0x2c00
	ds_read_b64_tr_b16 v[96:97], v206 offset:0x3400
	ds_read_b64_tr_b16 v[98:99], v206 offset:0x3c00
	s_waitcnt lgkmcnt(8)
	v_mfma_f32_32x32x16_bf16 v[36:51], v[68:71], v[164:167], v[36:51]
	v_mfma_f32_32x32x16_bf16 v[36:51], v[72:75], v[168:171], v[36:51]
	v_mfma_f32_32x32x16_bf16 v[36:51], v[80:83], v[240:243], v[36:51]
	v_mfma_f32_32x32x16_bf16 v[36:51], v[76:79], v[244:247], v[36:51]
	ds_read_b64_tr_b16 v[164:165], v206 offset:0x600
	ds_read_b64_tr_b16 v[166:167], v206 offset:0xe00
	ds_read_b64_tr_b16 v[168:169], v206 offset:0x1600
	ds_read_b64_tr_b16 v[170:171], v206 offset:0x1e00
	ds_read_b64_tr_b16 v[240:241], v206 offset:0x2600
	ds_read_b64_tr_b16 v[242:243], v206 offset:0x2e00
	ds_read_b64_tr_b16 v[244:245], v206 offset:0x3600
	ds_read_b64_tr_b16 v[246:247], v206 offset:0x3e00
	s_waitcnt lgkmcnt(8)
	v_mfma_f32_32x32x16_bf16 v[20:35], v[68:71], v[84:87], v[20:35]
	v_mfma_f32_32x32x16_bf16 v[20:35], v[72:75], v[88:91], v[20:35]
	v_mfma_f32_32x32x16_bf16 v[20:35], v[80:83], v[92:95], v[20:35]
	v_mfma_f32_32x32x16_bf16 v[20:35], v[76:79], v[96:99], v[20:35]
	s_waitcnt lgkmcnt(0)
	v_mfma_f32_32x32x16_bf16 v[4:19], v[68:71], v[164:167], v[4:19]
	v_mfma_f32_32x32x16_bf16 v[4:19], v[72:75], v[168:171], v[4:19]
	v_mfma_f32_32x32x16_bf16 v[4:19], v[80:83], v[240:243], v[4:19]
	v_mfma_f32_32x32x16_bf16 v[4:19], v[76:79], v[244:247], v[4:19]
	s_cmp_eq_u32 s100, 0
	s_cbranch_scc1 .Lmy_tail_s0
	s_cmp_eq_u32 s99, 2
	s_cbranch_scc1 .Lmy_done_s0
	s_branch .Lmy_ret_s0
.Lmy_defer_s0:
	s_mov_b32 s99, 1
	s_mov_b32 s98, s95
.Lmy_tail_s0:
	s_add_i32 s4, s81, 1
	s_andn2_b64 vcc, exec, s[0:1]
	s_cbranch_vccz .Lmy_exit_s0
	s_mov_b32 s81, s4
	v_mov_b32_e32 v198, v2
	s_mov_b32 s7, s96
	s_mov_b32 s95, s91
	s_mov_b32 s6, s77
	s_branch .LBB0_866
.Lmy_exit_s0:
	s_cmp_eq_u32 s99, 1
	s_cbranch_scc0 .Lmy_done_s0
	s_mov_b32 s99, 2
	s_branch .Lmy_pv_s0
.Lmy_done_s0:
	s_mov_b32 s99, 0

; #define TWAIT() do { asm volatile("s_waitcnt vmcnt(0)" ::: "memory"); __syncthreads(); } while (0)
; template <int VAR>
; __device__ __forceinline__ void nsa_attn_mfma(Frame& F, bf16* Y) {
;     ...
;       if (VAR < 5) for (;;) {
;         const int kbuf = it & 1;
;         TWAIT();
;         const int kbn = tiles ? 31 - __builtin_clz(tiles) : -1; const int vbn = (vbuf == 2) ? 0 : vbuf + 1;
;         if (kbn >= 0) { tiles &= ~(1u << kbn); TDMA(kgp + (size_t)kbn * 64 * NSA_NP, vgp + (size_t)kbn * 64 * NSA_NP, NSA_NP, kbuf ^ 1, vbn); }
;         else if (br == 0) TDMA(kgp + (size_t)cur * 64 * NSA_NP + (NSA_KW - NSA_KS), vgp + (size_t)cur * 64 * NSA_NP + (NSA_VW - NSA_VS), NSA_NP, kbuf ^ 1, vbn);
.LBB0_882:
	s_and_b32 s9, s81, 1
	s_cmp_eq_u32 s7, 0
	s_waitcnt vmcnt(0)
	s_cselect_b64 s[0:1], -1, 0
	s_add_i32 s4, s91, 1
	s_cmp_lg_u32 s91, 2
	s_cselect_b32 s10, s4, 0
	s_cmp_lg_u32 s7, 0
	s_barrier
	s_cmp_eq_u32 s99, 1
	s_cbranch_scc1 .Lmy_pv_w0
.Lmy_ret_w0:
	s_cmp_lg_u32 s7, 0
	s_cbranch_scc1 .LBB0_884
	s_lshl_b32 s8, s9, 14
	s_mov_b64 s[4:5], 0
	s_branch .LBB0_885

; __device__ __forceinline__ float swapmax(float x) { auto rr = __builtin_amdgcn_permlane32_swap(__float_as_uint(x), __float_as_uint(x), false, false); return fmaxf(__uint_as_float(rr[0]), __uint_as_float(rr[1])); }
; __device__ __forceinline__ float swapsum(float x) { auto rr = __builtin_amdgcn_permlane32_swap(__float_as_uint(x), __float_as_uint(x), false, false); return __uint_as_float(rr[0]) + __uint_as_float(rr[1]); }
; __device__ __forceinline__ void softmax_step(f32x16& p0, f32x16& p1, float& m, float& l, float& alpha, bf16x8& pa0, bf16x8& pa1, bf16x8& pa2, bf16x8& pa3) {
;   float pmax = p0[0];
; #pragma unroll
;   for (int r = 1; r < 16; ++r) pmax = fmaxf(pmax, p0[r]);
; #pragma unroll
;   for (int r = 0; r < 16; ++r) pmax = fmaxf(pmax, p1[r]);
;   pmax = swapmax(pmax);
;   if (__all(pmax - m <= THR2)) { alpha = 1.f; }
;   else { const float mn = fmaxf(m, pmax); alpha = __builtin_amdgcn_exp2f(m - mn); m = mn; }
;   float ps = 0.f;
; #pragma unroll
;   for (int r = 0; r < 16; ++r) { p0[r] = __builtin_amdgcn_exp2f(p0[r] - m); ps += p0[r]; }
; #pragma unroll
;   for (int r = 0; r < 16; ++r) { p1[r] = __builtin_amdgcn_exp2f(p1[r] - m); ps += p1[r]; }
;   ps = swapsum(ps);
;   l = l * alpha + ps;
;   PK4(p0, 0, pa0); PK4(p0, 8, pa1); PK4(p1, 0, pa2); PK4(p1, 8, pa3);
; }
.LBB0_889:
	v_max_f32_e32 v82, v155, v155
	v_max_f32_e32 v83, v154, v154
	v_max_f32_e32 v82, v83, v82
	v_max3_f32 v82, v82, v86, v87
	v_max3_f32 v82, v82, v88, v89
	v_max3_f32 v82, v82, v90, v91
	v_max3_f32 v82, v82, v92, v93
	v_max3_f32 v82, v82, v94, v95
	v_max3_f32 v82, v82, v96, v97
	v_max3_f32 v82, v82, v80, v81
	v_max3_f32 v82, v82, v84, v85
	v_max3_f32 v82, v82, v158, v76
	v_max3_f32 v82, v82, v77, v72
	v_max3_f32 v82, v82, v73, v78
	v_max3_f32 v82, v82, v79, v74
	v_max3_f32 v82, v82, v75, v68
	v_max3_f32 v82, v82, v69, v70
	v_max3_f32 v82, v82, v71, v2
	v_mov_b32_e32 v83, v82
	s_nop 1
	v_permlane32_swap_b32_e32 v82, v83
	v_max_f32_e32 v83, v83, v83
	v_max_f32_e32 v82, v82, v82
	v_max_f32_e32 v82, v82, v83
	v_sub_f32_e32 v83, v82, v156
	v_cmp_ge_f32_e32 vcc, s88, v83
	v_max_f32_e32 v98, v156, v156
	s_cmp_eq_u64 vcc, exec
	v_max_f32_e32 v82, v98, v82
	s_cselect_b64 vcc, -1, 0
	v_sub_f32_e32 v98, v156, v82
	v_cndmask_b32_e32 v156, v82, v156, vcc
	v_sub_f32_e32 v82, v154, v156
	v_exp_f32_e32 v82, v82
	v_sub_f32_e32 v83, v155, v156
	v_exp_f32_e32 v83, v83
	v_sub_f32_e32 v86, v86, v156
	v_exp_f32_e32 v86, v86
	v_sub_f32_e32 v87, v87, v156
	v_exp_f32_e32 v87, v87
	v_sub_f32_e32 v88, v88, v156
	v_add_f32_e32 v99, 0, v82
	v_exp_f32_e32 v88, v88
	v_sub_f32_e32 v89, v89, v156
	v_add_f32_e32 v99, v83, v99
	v_exp_f32_e32 v89, v89
	v_sub_f32_e32 v90, v90, v156
	v_add_f32_e32 v99, v86, v99
	v_exp_f32_e32 v90, v90
	v_sub_f32_e32 v91, v91, v156
	v_add_f32_e32 v99, v87, v99
	v_exp_f32_e32 v91, v91
	v_sub_f32_e32 v92, v92, v156
	v_add_f32_e32 v99, v88, v99
	v_exp_f32_e32 v92, v92
	v_sub_f32_e32 v93, v93, v156
	v_add_f32_e32 v99, v89, v99
	v_exp_f32_e32 v93, v93
	v_sub_f32_e32 v94, v94, v156
	v_add_f32_e32 v99, v90, v99
	v_exp_f32_e32 v94, v94
	v_sub_f32_e32 v95, v95, v156
	v_add_f32_e32 v99, v91, v99
	v_exp_f32_e32 v95, v95
	v_sub_f32_e32 v96, v96, v156
	v_add_f32_e32 v99, v92, v99
	v_exp_f32_e32 v96, v96
	v_sub_f32_e32 v97, v97, v156
	v_add_f32_e32 v99, v93, v99
	v_exp_f32_e32 v97, v97
	v_sub_f32_e32 v80, v80, v156
	v_add_f32_e32 v99, v94, v99
	v_exp_f32_e32 v80, v80
	v_sub_f32_e32 v81, v81, v156
	v_add_f32_e32 v99, v95, v99
	v_exp_f32_e32 v81, v81
	v_sub_f32_e32 v84, v84, v156
	v_add_f32_e32 v99, v96, v99
	v_exp_f32_e32 v154, v84
	v_sub_f32_e32 v84, v85, v156
	v_add_f32_e32 v99, v97, v99
	v_exp_f32_e32 v85, v84
	v_sub_f32_e32 v84, v158, v156
	v_add_f32_e32 v99, v80, v99
	v_exp_f32_e32 v155, v84
	v_sub_f32_e32 v76, v76, v156
	v_add_f32_e32 v99, v81, v99
	v_exp_f32_e32 v76, v76
	v_sub_f32_e32 v77, v77, v156
	v_add_f32_e32 v84, v154, v99
	v_exp_f32_e32 v77, v77
	v_sub_f32_e32 v72, v72, v156
	v_add_f32_e32 v84, v85, v84
	v_exp_f32_e32 v99, v72
	v_sub_f32_e32 v72, v73, v156
	v_add_f32_e32 v84, v155, v84
	v_exp_f32_e32 v158, v72
	v_sub_f32_e32 v72, v78, v156
	v_add_f32_e32 v84, v76, v84
	v_exp_f32_e32 v78, v72
	v_sub_f32_e32 v73, v79, v156
	v_add_f32_e32 v72, v77, v84
	v_exp_f32_e32 v79, v73
	v_sub_f32_e32 v73, v74, v156
	v_add_f32_e32 v72, v99, v72
	v_exp_f32_e32 v159, v73
	v_sub_f32_e32 v73, v75, v156
	v_add_f32_e32 v72, v158, v72
	v_exp_f32_e32 v160, v73
	v_sub_f32_e32 v68, v68, v156
	v_add_f32_e32 v72, v78, v72
	v_exp_f32_e32 v161, v68
	v_sub_f32_e32 v69, v69, v156
	v_add_f32_e32 v68, v79, v72
	v_exp_f32_e32 v162, v69
	v_sub_f32_e32 v69, v70, v156
	v_add_f32_e32 v68, v159, v68
	v_exp_f32_e32 v163, v69
	v_sub_f32_e32 v69, v71, v156
	v_add_f32_e32 v68, v160, v68
	v_exp_f32_e32 v164, v69
	v_sub_f32_e32 v2, v2, v156
	v_add_f32_e32 v68, v161, v68
	v_exp_f32_e32 v165, v2
	v_exp_f32_e32 v98, v98
	v_add_f32_e32 v2, v162, v68
	v_add_f32_e32 v2, v163, v2
	v_add_f32_e32 v2, v164, v2
	v_add_f32_e32 v2, v165, v2
	v_cndmask_b32_e64 v98, v98, 1.0, vcc
	v_mov_b32_e32 v84, v2
	v_cvt_pk_bf16_f32 v68, v82, v83
	v_cvt_pk_bf16_f32 v69, v86, v87
	v_cvt_pk_bf16_f32 v70, v88, v89
	v_cvt_pk_bf16_f32 v71, v90, v91
	v_cvt_pk_bf16_f32 v72, v92, v93
	v_cvt_pk_bf16_f32 v73, v94, v95
	v_cvt_pk_bf16_f32 v74, v96, v97
	v_cvt_pk_bf16_f32 v75, v80, v81
	v_cvt_pk_bf16_f32 v80, v154, v85
	v_cvt_pk_bf16_f32 v81, v155, v76
	v_cvt_pk_bf16_f32 v82, v77, v99
	v_cvt_pk_bf16_f32 v83, v158, v78
	v_cvt_pk_bf16_f32 v76, v79, v159
	v_cvt_pk_bf16_f32 v77, v160, v161
	v_cvt_pk_bf16_f32 v78, v162, v163
	v_cvt_pk_bf16_f32 v79, v164, v165
	s_nop 1
	v_permlane32_swap_b32_e32 v2, v84
	v_permlane32_swap_b32_e32 v68, v70
	v_permlane32_swap_b32_e32 v69, v71
	v_permlane32_swap_b32_e32 v72, v74
	v_permlane32_swap_b32_e32 v73, v75
	v_permlane32_swap_b32_e32 v80, v82
	v_permlane32_swap_b32_e32 v81, v83
	v_permlane32_swap_b32_e32 v76, v78
	v_permlane32_swap_b32_e32 v77, v79
	v_add_f32_e32 v2, v2, v84
	v_fmac_f32_e32 v2, v157, v98
	s_cmp_eq_u32 s100, 0
	s_cbranch_scc0 .Lmy_defer_w0
	s_mov_b32 s98, s91
; #define SBAR() __builtin_amdgcn_sched_barrier(0)
; #define PV_RD(D0, L0, H0, L1, H1, L2, H2, L3, H3) do { L0 = tr_read<v_rd_off(D0, 0, 0)>(vb); H0 = tr_read<v_rd_off(D0, 0, 1)>(vb); L1 = tr_read<v_rd_off(D0, 1, 0)>(vb); H1 = tr_read<v_rd_off(D0, 1, 1)>(vb); \
;     L2 = tr_read<v_rd_off(D0, 2, 0)>(vb); H2 = tr_read<v_rd_off(D0, 2, 1)>(vb); L3 = tr_read<v_rd_off(D0, 3, 0)>(vb); H3 = tr_read<v_rd_off(D0, 3, 1)>(vb); } while (0)
; #define PV_MM(OD, L0, H0, L1, H1, L2, H2, L3, H3) do { OD = __builtin_amdgcn_mfma_f32_32x32x16_bf16(pa0, PV_PK(L0, H0), OD, 0, 0, 0); OD = __builtin_amdgcn_mfma_f32_32x32x16_bf16(pa1, PV_PK(L1, H1), OD, 0, 0, 0); \
;     OD = __builtin_amdgcn_mfma_f32_32x32x16_bf16(pa2, PV_PK(L2, H2), OD, 0, 0, 0); OD = __builtin_amdgcn_mfma_f32_32x32x16_bf16(pa3, PV_PK(L3, H3), OD, 0, 0, 0); } while (0)
; __device__ __forceinline__ void pv_d0(f32x16* o, int vb, bf16x8 pa0, bf16x8 pa1, bf16x8 pa2, bf16x8 pa3) {
;   s16x4 al0, ah0, al1, ah1, al2, ah2, al3, ah3, bl0, bh0, bl1, bh1, bl2, bh2, bl3, bh3;
;   PV_RD(0, al0, ah0, al1, ah1, al2, ah2, al3, ah3);
;   PV_RD(1, bl0, bh0, bl1, bh1, bl2, bh2, bl3, bh3);
;   asm volatile("s_waitcnt lgkmcnt(8)" ::: "memory"); SBAR();
;   PV_MM(o[0], al0, ah0, al1, ah1, al2, ah2, al3, ah3); SBAR();
;   PV_RD(2, al0, ah0, al1, ah1, al2, ah2, al3, ah3);
;   asm volatile("s_waitcnt lgkmcnt(8)" ::: "memory"); SBAR();
;   PV_MM(o[1], bl0, bh0, bl1, bh1, bl2, bh2, bl3, bh3); SBAR();
;   PV_RD(3, bl0, bh0, bl1, bh1, bl2, bh2, bl3, bh3);
;   asm volatile("s_waitcnt lgkmcnt(8)" ::: "memory"); SBAR();
;   PV_MM(o[2], al0, ah0, al1, ah1, al2, ah2, al3, ah3); SBAR();
;   asm volatile("s_waitcnt lgkmcnt(0)" ::: "memory"); SBAR();
;   PV_MM(o[3], bl0, bh0, bl1, bh1, bl2, bh2, bl3, bh3);
; }
.Lmy_pv_w0:
	v_cmp_gt_f32_e32 vcc, 1.0, v98
	s_cbranch_vccz .LBB0_893
	s_and_saveexec_b64 s[4:5], s[2:3]
	ds_write_b32 v193, v98 offset:128
	s_or_b64 exec, exec, s[4:5]
	s_waitcnt lgkmcnt(0)
	ds_read_b128 v[86:89], v139 offset:224
	ds_read_b128 v[90:93], v139 offset:192
	ds_read_b128 v[94:97], v139 offset:160
	ds_read_b128 v[158:161], v139 offset:128
	s_waitcnt lgkmcnt(0)
	s_waitcnt lgkmcnt(0)
	v_pk_mul_f32 v[66:67], v[66:67], v[88:89]
	v_pk_mul_f32 v[62:63], v[62:63], v[92:93]
	v_pk_mul_f32 v[58:59], v[58:59], v[96:97]
	v_pk_mul_f32 v[54:55], v[54:55], v[160:161]
	v_pk_mul_f32 v[64:65], v[64:65], v[86:87]
	v_pk_mul_f32 v[60:61], v[60:61], v[90:91]
	v_pk_mul_f32 v[56:57], v[56:57], v[94:95]
	v_pk_mul_f32 v[52:53], v[52:53], v[158:159]
	v_pk_mul_f32 v[50:51], v[50:51], v[88:89]
	v_pk_mul_f32 v[46:47], v[46:47], v[92:93]
	v_pk_mul_f32 v[42:43], v[42:43], v[96:97]
	v_pk_mul_f32 v[38:39], v[38:39], v[160:161]
	v_pk_mul_f32 v[48:49], v[48:49], v[86:87]
	v_pk_mul_f32 v[44:45], v[44:45], v[90:91]
	v_pk_mul_f32 v[40:41], v[40:41], v[94:95]
	v_pk_mul_f32 v[36:37], v[36:37], v[158:159]
	v_pk_mul_f32 v[34:35], v[34:35], v[88:89]
	v_pk_mul_f32 v[30:31], v[30:31], v[92:93]
	v_pk_mul_f32 v[26:27], v[26:27], v[96:97]
	v_pk_mul_f32 v[22:23], v[22:23], v[160:161]
	v_pk_mul_f32 v[32:33], v[32:33], v[86:87]
	v_pk_mul_f32 v[28:29], v[28:29], v[90:91]
	v_pk_mul_f32 v[24:25], v[24:25], v[94:95]
	v_pk_mul_f32 v[20:21], v[20:21], v[158:159]
	v_pk_mul_f32 v[18:19], v[18:19], v[88:89]
	v_pk_mul_f32 v[14:15], v[14:15], v[92:93]
	v_pk_mul_f32 v[10:11], v[10:11], v[96:97]
	v_pk_mul_f32 v[6:7], v[6:7], v[160:161]
	v_pk_mul_f32 v[16:17], v[16:17], v[86:87]
	v_pk_mul_f32 v[12:13], v[12:13], v[90:91]
	v_pk_mul_f32 v[8:9], v[8:9], v[94:95]
	v_pk_mul_f32 v[4:5], v[4:5], v[158:159]
.LBB0_893:
	v_lshl_add_u32 v154, s98, 14, v192
	ds_read_b64_tr_b16 v[84:85], v154 offset:0
	ds_read_b64_tr_b16 v[86:87], v154 offset:0x800
	ds_read_b64_tr_b16 v[88:89], v154 offset:0x1000
	ds_read_b64_tr_b16 v[90:91], v154 offset:0x1800
	ds_read_b64_tr_b16 v[92:93], v154 offset:0x2000
	ds_read_b64_tr_b16 v[94:95], v154 offset:0x2800
	ds_read_b64_tr_b16 v[96:97], v154 offset:0x3000
	ds_read_b64_tr_b16 v[98:99], v154 offset:0x3800
	ds_read_b64_tr_b16 v[158:159], v154 offset:0x200
	ds_read_b64_tr_b16 v[160:161], v154 offset:0xa00
	ds_read_b64_tr_b16 v[162:163], v154 offset:0x1200
	ds_read_b64_tr_b16 v[164:165], v154 offset:0x1a00
	ds_read_b64_tr_b16 v[166:167], v154 offset:0x2200
	ds_read_b64_tr_b16 v[168:169], v154 offset:0x2a00
	ds_read_b64_tr_b16 v[196:197], v154 offset:0x3200
	ds_read_b64_tr_b16 v[198:199], v154 offset:0x3a00
	s_waitcnt lgkmcnt(8)
	v_mfma_f32_32x32x16_bf16 v[52:67], v[68:71], v[84:87], v[52:67]
	v_mfma_f32_32x32x16_bf16 v[52:67], v[72:75], v[88:91], v[52:67]
	v_mfma_f32_32x32x16_bf16 v[52:67], v[80:83], v[92:95], v[52:67]
	v_mfma_f32_32x32x16_bf16 v[52:67], v[76:79], v[96:99], v[52:67]
	ds_read_b64_tr_b16 v[84:85], v154 offset:0x400
	ds_read_b64_tr_b16 v[86:87], v154 offset:0xc00
	ds_read_b64_tr_b16 v[88:89], v154 offset:0x1400
	ds_read_b64_tr_b16 v[90:91], v154 offset:0x1c00
	ds_read_b64_tr_b16 v[92:93], v154 offset:0x2400
	ds_read_b64_tr_b16 v[94:95], v154 offset:0x2c00
	ds_read_b64_tr_b16 v[96:97], v154 offset:0x3400
	ds_read_b64_tr_b16 v[98:99], v154 offset:0x3c00
	s_waitcnt lgkmcnt(8)
	v_mfma_f32_32x32x16_bf16 v[36:51], v[68:71], v[158:161], v[36:51]
	v_mfma_f32_32x32x16_bf16 v[36:51], v[72:75], v[162:165], v[36:51]
	v_mfma_f32_32x32x16_bf16 v[36:51], v[80:83], v[166:169], v[36:51]
	v_mfma_f32_32x32x16_bf16 v[36:51], v[76:79], v[196:199], v[36:51]
	ds_read_b64_tr_b16 v[158:159], v154 offset:0x600
	ds_read_b64_tr_b16 v[160:161], v154 offset:0xe00
	ds_read_b64_tr_b16 v[162:163], v154 offset:0x1600
	ds_read_b64_tr_b16 v[164:165], v154 offset:0x1e00
	ds_read_b64_tr_b16 v[166:167], v154 offset:0x2600
	ds_read_b64_tr_b16 v[168:169], v154 offset:0x2e00
	ds_read_b64_tr_b16 v[196:197], v154 offset:0x3600
	ds_read_b64_tr_b16 v[198:199], v154 offset:0x3e00
	s_waitcnt lgkmcnt(8)
	v_mfma_f32_32x32x16_bf16 v[20:35], v[68:71], v[84:87], v[20:35]
	v_mfma_f32_32x32x16_bf16 v[20:35], v[72:75], v[88:91], v[20:35]
	v_mfma_f32_32x32x16_bf16 v[20:35], v[80:83], v[92:95], v[20:35]
	v_mfma_f32_32x32x16_bf16 v[20:35], v[76:79], v[96:99], v[20:35]
	s_waitcnt lgkmcnt(0)
	v_mfma_f32_32x32x16_bf16 v[4:19], v[68:71], v[158:161], v[4:19]
	v_mfma_f32_32x32x16_bf16 v[4:19], v[72:75], v[162:165], v[4:19]
	v_mfma_f32_32x32x16_bf16 v[4:19], v[80:83], v[166:169], v[4:19]
	v_mfma_f32_32x32x16_bf16 v[4:19], v[76:79], v[196:199], v[4:19]
	s_cmp_eq_u32 s100, 0
	s_cbranch_scc1 .Lmy_tail_w0
	s_cmp_eq_u32 s99, 2
	s_cbranch_scc1 .Lmy_done_w0
	s_branch .Lmy_ret_w0
.Lmy_defer_w0:
	s_mov_b32 s99, 1
	s_mov_b32 s98, s91
.Lmy_tail_w0:
	s_add_i32 s81, s81, 1
	s_andn2_b64 vcc, exec, s[0:1]
	s_cbranch_vccz .Lmy_exit_w0
	v_mov_b32_e32 v157, v2
	s_mov_b32 s7, s12
	s_mov_b32 s91, s10
	s_mov_b32 s6, s11
	s_branch .LBB0_882

; template <class CM>
; __device__ __forceinline__ void p0_transpose_matrix(Frame& F, const float* W, int K, int N, bf16* WT, int nblk, CM colmap, int& it0, const float* kgain = nullptr) {
;     ...
;     for (int r = first; r < nitems; r += F.ngw) {
;         const int kb = r / nblk, nb = r % nblk;
;         p0_transpose_item(W, K, N, WT, kb, colmap(nb), nb * 32, scr, F.lane, kgain);
; __device__ __forceinline__ void p0_deferred(Frame& F, int my, int nconv, int part = -1) {
;     const int gw0 = F.gw, ngw0 = F.ngw; F.gw = my * NWAVES + F.wave; F.ngw = nconv * NWAVES;
;     int it0 = 0;
;     if (part < 0 || part == 0) p0_transpose_matrix(F, FIN(F, 18), DM, DM, (bf16*)FW(F, WS_W_HG_OUT), DM / 32, [](int nb) { return nb * 32; }, it0);
;     if (part < 0 || part == 1) p0_transpose_matrix(F, FIN(F, 3) + (size_t)DM * 11360, DM, 11360, (bf16*)FW(F, WS_W_NSA_IN) + (size_t)NSA_NP * DM, NSA_NP / 32,
;         [](int nb) { const int n = nb * 32; return n < 7168 ? n : (n < 11264 ? n + 96 : (n < 11360 ? n - 4096 : -1)); }, it0, FIN(F, 1) + 3 * DM);
.LBB0_1691:
	s_or_b64 exec, exec, s[4:5]
	v_readlane_b32 s6, v254, 7
	v_readlane_b32 s7, v254, 8
	s_load_dwordx2 s[4:5], s[6:7], 0x8
	s_nop 0
	s_load_dwordx2 s[6:7], s[6:7], 0x18
	v_lshlrev_b32_e32 v2, 2, v16
	v_mov_b32_e32 v3, 0
	v_mov_b32_e32 v15, v3
	s_waitcnt lgkmcnt(0)
	v_lshl_add_u64 v[4:5], s[4:5], 0, v[2:3]
	s_mov_b64 s[4:5], 0xc000
	v_lshlrev_b32_e32 v2, 1, v16
	v_lshl_add_u64 v[18:19], v[4:5], 0, s[4:5]
	v_lshl_add_u64 v[4:5], s[70:71], 0, v[2:3]
	s_mov_b64 s[4:5], 0x5c00000
	v_lshl_add_u64 v[20:21], v[4:5], 0, s[4:5]
	v_lshl_add_u64 v[4:5], s[6:7], 0, v[14:15]
	s_mov_b64 s[4:5], 0xb180000
	v_lshl_add_u64 v[22:23], v[4:5], 0, s[4:5]
	s_mov_b32 s11, 0xb180
	v_add_u32_e32 v32, 0x400, v30
	v_add_u32_e32 v33, 0x800, v30
	v_add_u32_e32 v36, 0xc00, v30
	v_add_u32_e32 v37, 0x1000, v30
	v_add_u32_e32 v38, 0x1400, v30
	v_add_u32_e32 v39, 0x1800, v30
	v_add_u32_e32 v40, 0x1c00, v30
	v_mov_b32_e32 v2, v3
	v_mov_b32_e32 v4, v3
	v_mov_b32_e32 v5, v3
	s_branch .LBB0_1693
.LBB0_1692:
	s_waitcnt vmcnt(2)
	v_add_u32_e32 v6, 24, v26
	v_ashrrev_i32_e32 v7, 31, v6
	v_lshlrev_b64 v[6:7], 13, v[6:7]
	v_lshl_add_u64 v[6:7], v[24:25], 0, v[6:7]
	global_store_dwordx4 v[6:7], v[14:17], off
	s_waitcnt lgkmcnt(0)
	s_add_i32 s2, s9, 0x400
	s_add_i32 s10, s10, 0x8000
	s_cmpk_lt_i32 s9, 0x5600
	s_mov_b32 s9, s2
	s_cbranch_scc0 .LBB0_1709

; __device__ __forceinline__ unsigned pk2(float lo, float hi) { unsigned r; asm volatile("v_cvt_pk_bf16_f32 %0, %1, %2" : "=v"(r) : "v"(lo), "v"(hi)); return r; }
; __device__ __forceinline__ unsigned xb_add(unsigned* p, unsigned v) { return __hip_atomic_fetch_add(p, v, __ATOMIC_RELAXED, __HIP_MEMORY_SCOPE_AGENT); }
; #define GEMM_WOUT_SCHED(SCHED, S_init) do { \
;         pg8::Gemm g_{(const pg8::bf16_t*)FW(F, WS_Y), (const pg8::bf16_t*)FW(F, WS_W_HG_OUT), MTOK, DM, DM, DM, 0}; SCHED S_ S_init; \
;         pg8::EpiBf16<0> E_{(pg8::bf16_t*)FW(F, WS_YO), DM, nullptr, 0, 0, 1.f}; \
;         pg8::gemm_phase<pg8::EpiBf16<0>, SCHED, true, true>((PG8_LAS unsigned char*)lds + RING_OFF, g_, S_, E_); } while (0)
; __device__ __forceinline__ void p0_transpose_item(const float* W, int K, int N, bf16* WT, int kb, int src_col0, int dst_row0, float* scr, int lane, const float* kgain = nullptr) {
;     ...
;     for (int j = 0; j < 4; ++j) { const int n = (lane >> 3) + 8 * j; const float* s = scr + (8 * c) * 33 + n;
;         v4u o;
;         if (src_col0 >= 0) { o.x = pk2(s[0 * 33] * g0.x, s[1 * 33] * g0.y); o.y = pk2(s[2 * 33] * g0.z, s[3 * 33] * g0.w); o.z = pk2(s[4 * 33] * g1.x, s[5 * 33] * g1.y); o.w = pk2(s[6 * 33] * g1.z, s[7 * 33] * g1.w); }
;         else { o.x = 0u; o.y = 0u; o.z = 0u; o.w = 0u; }
;         *(v4u*)(WT + (size_t)(dst_row0 + n) * K + k0 + 8 * c) = o; }
;     __builtin_amdgcn_s_waitcnt(0xC07F); asm volatile("" ::: "memory");
; __global__ void __launch_bounds__(NTHREADS, 2) fwd_kernel(Args args) {
;     ...
;                 asm volatile("s_waitcnt vmcnt(0)" ::: "memory"); __syncthreads();
;                 if (F.tid == 0) { __builtin_amdgcn_fence(__ATOMIC_RELEASE, "agent"); asm volatile("s_waitcnt vmcnt(0)" ::: "memory"); (void)xb_add(ctl + CW_WOF, 1u); }
;                 p0_deferred(F, j, 128, 1);
;                 __syncthreads();
;                 GEMM_WOUT_SCHED(SchedEarly, ({j, ctl + CW_HGF, ctl + CW_WOF, barw})); } }
.LBB0_1707:
	v_mov_b32_e32 v14, 0
	s_andn2_b64 vcc, exec, s[6:7]
	v_mov_b32_e32 v15, 0
	v_mov_b32_e32 v16, 0
	v_mov_b32_e32 v17, 0
	s_cbranch_vccnz .LBB0_1692
	ds_read2_b32 v[14:15], v31 offset0:16 offset1:49
	v_lshlrev_b64 v[28:29], 13, v[28:29]
	v_lshl_add_u64 v[28:29], v[24:25], 0, v[28:29]
	s_waitcnt vmcnt(1) lgkmcnt(0)
	v_mul_f32_e32 v14, v10, v14
	v_mul_f32_e32 v15, v11, v15
	v_cvt_pk_bf16_f32 v14, v14, v15
	ds_read2_b32 v[16:17], v31 offset0:82 offset1:115
	s_waitcnt lgkmcnt(0)
	v_mul_f32_e32 v15, v12, v16
	v_mul_f32_e32 v16, v13, v17
	v_cvt_pk_bf16_f32 v15, v15, v16
	ds_read2_b32 v[16:17], v31 offset0:148 offset1:181
	s_waitcnt lgkmcnt(0)
	v_mul_f32_e32 v16, v6, v16
	v_mul_f32_e32 v17, v7, v17
	v_cvt_pk_bf16_f32 v16, v16, v17
	ds_read2_b32 v[42:43], v31 offset0:214 offset1:247
	s_waitcnt lgkmcnt(0)
	v_mul_f32_e32 v17, v8, v42
	v_mul_f32_e32 v27, v9, v43
	v_cvt_pk_bf16_f32 v17, v17, v27
	ds_read2_b32 v[42:43], v31 offset0:24 offset1:57
	global_store_dwordx4 v[28:29], v[14:17], off
	s_waitcnt lgkmcnt(0)
	v_mul_f32_e32 v10, v10, v42
	v_mul_f32_e32 v11, v11, v43
	v_cvt_pk_bf16_f32 v14, v10, v11
	ds_read2_b32 v[10:11], v31 offset0:90 offset1:123
	s_waitcnt lgkmcnt(0)
	v_mul_f32_e32 v10, v12, v10
	v_mul_f32_e32 v11, v13, v11
	v_cvt_pk_bf16_f32 v15, v10, v11
	ds_read2_b32 v[10:11], v31 offset0:156 offset1:189
	s_waitcnt lgkmcnt(0)
	v_mul_f32_e32 v6, v6, v10
	v_mul_f32_e32 v7, v7, v11
	v_cvt_pk_bf16_f32 v16, v6, v7
	ds_read2_b32 v[6:7], v31 offset0:222 offset1:255
	s_waitcnt lgkmcnt(0)
	v_mul_f32_e32 v6, v8, v6
	v_mul_f32_e32 v7, v9, v7
	v_cvt_pk_bf16_f32 v17, v6, v7
	s_branch .LBB0_1692
.LBB0_1709:
	v_mov_b32_e32 v2, 0
	s_barrier
	global_load_dword v3, v2, s[70:71] offset:768 sc1
	s_movk_i32 s9, 0x7f
	v_readfirstlane_b32 s12, v0
	s_waitcnt vmcnt(0)
	v_cmp_lt_u32_e32 vcc, s9, v3
	s_cbranch_vccnz .LBB0_1722
	s_mov_b32 s10, 1
	s_branch .LBB0_1712

; __device__ __forceinline__ unsigned xb_ld(unsigned* p)              { return __hip_atomic_load(p, __ATOMIC_RELAXED, __HIP_MEMORY_SCOPE_AGENT); }
; __device__ __forceinline__ void xcd_barrier_complete(unsigned* bar, unsigned x, unsigned& nloc, unsigned& nx) {
;     const unsigned G = gridDim.x * gridDim.y * gridDim.z;
;     unsigned sum, cnt, mine, sp = 0u;
;     for (;;) {
;         sum = 0u; cnt = 0u; mine = 0u;
; #pragma unroll
;         for (unsigned j = 0; j < 16; ++j) { const unsigned c = xb_ld(&bar[XB_XCNT(j)]); sum += c; cnt += (c > 0u) ? 1u : 0u; mine = (j == x) ? c : mine; }
;         if (sum == G) break;
; __device__ __forceinline__ void xcd_barrier(const XcdBarrier& b) {
;     asm volatile("s_waitcnt vmcnt(0)" ::: "memory");
;     __syncthreads();
;     if (threadIdx.x == 0) {
;         unsigned* bar = b.bar;
;         __builtin_amdgcn_s_waitcnt(0);
;         unsigned nloc = b.st[0], nx = b.st[1];
;         if (nloc == 0u) { xcd_barrier_complete(bar, b.x, nloc, nx); b.st[0] = nloc; b.st[1] = nx; }
.LBB0_1798:
	s_barrier
.LBB0_1799:
	s_and_b64 s[0:1], s[92:93], s[88:89]
	s_andn2_b64 vcc, exec, s[0:1]
	s_cbranch_vccnz .LBB0_1849
	s_waitcnt vmcnt(0)
	v_cmp_eq_u32_e32 vcc, 0, v0
	s_waitcnt vmcnt(0) lgkmcnt(0)
	s_barrier
	s_and_saveexec_b64 s[0:1], vcc
	s_cbranch_execz .LBB0_1848
	v_mov_b32_e32 v1, s84
	s_waitcnt vmcnt(0) expcnt(0) lgkmcnt(0)
	ds_read_b32 v3, v1
	ds_read_b32 v1, v1 offset:4
	s_waitcnt lgkmcnt(1)
	v_cmp_ne_u32_e32 vcc, 0, v3
	s_cbranch_vccnz .LBB0_1816
	v_readlane_b32 s2, v254, 4
	v_readlane_b32 s3, v254, 5
	s_load_dwordx2 s[6:7], s[2:3], 0x4
	s_add_u32 s2, s78, 0x1000
	s_addc_u32 s3, s79, 0
	s_add_u32 s4, s78, 0x1100
	s_addc_u32 s5, s79, 0
	s_waitcnt lgkmcnt(0)
	s_mul_i32 s16, s6, s83
	s_add_u32 s6, s78, 0x1200
	s_mul_i32 s16, s16, s7
	s_addc_u32 s7, s79, 0
	s_add_u32 s8, s78, 0x1300
	s_addc_u32 s9, s79, 0
	s_mov_b32 s17, 1
	v_mov_b32_e32 v17, 0
	s_branch .LBB0_1804

; #define TWAIT() do { asm volatile("s_waitcnt vmcnt(0)" ::: "memory"); __syncthreads(); } while (0)
; template <int VAR>
; __device__ __forceinline__ void nsa_attn_mfma(Frame& F, bf16* Y) {
;     ...
;       if (VAR < 5) for (;;) {
;         const int kbuf = it & 1;
;         TWAIT();
;         const int kbn = tiles ? 31 - __builtin_clz(tiles) : -1; const int vbn = (vbuf == 2) ? 0 : vbuf + 1;
;         if (kbn >= 0) { tiles &= ~(1u << kbn); TDMA(kgp + (size_t)kbn * 64 * NSA_NP, vgp + (size_t)kbn * 64 * NSA_NP, NSA_NP, kbuf ^ 1, vbn); }
;         else if (br == 0) TDMA(kgp + (size_t)cur * 64 * NSA_NP + (NSA_KW - NSA_KS), vgp + (size_t)cur * 64 * NSA_NP + (NSA_VW - NSA_VS), NSA_NP, kbuf ^ 1, vbn);
.LBB0_2422:
	s_add_i32 s90, s90, 1
	s_and_b32 s10, s90, 1
	s_cmp_eq_u32 s7, 0
	s_waitcnt vmcnt(0)
	s_cselect_b64 s[84:85], -1, 0
	s_add_i32 s4, s91, 1
	s_cmp_lg_u32 s91, 2
	s_cselect_b32 s87, s4, 0
	s_and_b64 vcc, exec, s[84:85]
	s_waitcnt lgkmcnt(0)
	s_barrier
	s_cmp_eq_u32 s99, 1
	s_cbranch_scc1 .Lmy_pv_s3
.Lmy_ret_s3:
	s_and_b64 vcc, exec, s[84:85]
	s_cbranch_vccz .LBB0_2424
	s_lshl_b32 s8, s10, 14
	s_xor_b32 s4, s8, 0x4000
	s_add_i32 s4, s95, s4
	s_lshl_b32 s9, s87, 14
	s_add_i32 s5, s95, s9
	s_mov_b32 m0, s4
	s_add_i32 s5, s5, 0x8000
	global_load_lds_dwordx4 v[156:157], off
	s_add_i32 m0, s4, 0x2000
	s_nop 0
	global_load_lds_dwordx4 v[158:159], off
	s_mov_b32 m0, s5
	s_mov_b64 s[4:5], 0
	global_load_lds_dwordx4 v[160:161], off
	s_branch .LBB0_2425

; __device__ __forceinline__ float swapmax(float x) { auto rr = __builtin_amdgcn_permlane32_swap(__float_as_uint(x), __float_as_uint(x), false, false); return fmaxf(__uint_as_float(rr[0]), __uint_as_float(rr[1])); }
; __device__ __forceinline__ float swapsum(float x) { auto rr = __builtin_amdgcn_permlane32_swap(__float_as_uint(x), __float_as_uint(x), false, false); return __uint_as_float(rr[0]) + __uint_as_float(rr[1]); }
; __device__ __forceinline__ void softmax_step(f32x16& p0, f32x16& p1, float& m, float& l, float& alpha, bf16x8& pa0, bf16x8& pa1, bf16x8& pa2, bf16x8& pa3) {
;   float pmax = p0[0];
; #pragma unroll
;   for (int r = 1; r < 16; ++r) pmax = fmaxf(pmax, p0[r]);
; #pragma unroll
;   for (int r = 0; r < 16; ++r) pmax = fmaxf(pmax, p1[r]);
;   pmax = swapmax(pmax);
;   if (__all(pmax - m <= THR2)) { alpha = 1.f; }
;   else { const float mn = fmaxf(m, pmax); alpha = __builtin_amdgcn_exp2f(m - mn); m = mn; }
;   float ps = 0.f;
; #pragma unroll
;   for (int r = 0; r < 16; ++r) { p0[r] = __builtin_amdgcn_exp2f(p0[r] - m); ps += p0[r]; }
; #pragma unroll
;   for (int r = 0; r < 16; ++r) { p1[r] = __builtin_amdgcn_exp2f(p1[r] - m); ps += p1[r]; }
;   ps = swapsum(ps);
;   l = l * alpha + ps;
;   PK4(p0, 0, pa0); PK4(p0, 8, pa1); PK4(p1, 0, pa2); PK4(p1, 8, pa3);
; }
.LBB0_2429:
	v_max_f32_e32 v81, v164, v164
	v_max_f32_e32 v82, v2, v2
	v_max_f32_e32 v81, v82, v81
	v_max3_f32 v81, v81, v165, v166
	v_max3_f32 v81, v81, v167, v168
	v_max3_f32 v81, v81, v169, v170
	v_max3_f32 v81, v81, v171, v92
	v_max3_f32 v81, v81, v93, v76
	v_max3_f32 v81, v81, v77, v78
	v_max3_f32 v81, v81, v79, v80
	v_max3_f32 v81, v81, v90, v91
	v_max3_f32 v81, v81, v88, v89
	v_max3_f32 v81, v81, v86, v87
	v_max3_f32 v81, v81, v84, v85
	v_max3_f32 v81, v81, v70, v71
	v_max3_f32 v81, v81, v72, v73
	v_max3_f32 v81, v81, v68, v69
	v_max3_f32 v81, v81, v74, v75
	v_mov_b32_e32 v82, v81
	s_nop 1
	v_permlane32_swap_b32_e32 v81, v82
	v_max_f32_e32 v82, v82, v82
	v_max_f32_e32 v81, v81, v81
	v_max_f32_e32 v81, v81, v82
	v_sub_f32_e32 v82, v81, v197
	v_max_f32_e32 v83, v197, v197
	v_cmp_ge_f32_e32 vcc, s72, v82
	v_max_f32_e32 v81, v83, v81
	s_cmp_eq_u64 vcc, exec
	v_sub_f32_e32 v83, v197, v81
	s_cselect_b64 vcc, -1, 0
	v_exp_f32_e32 v83, v83
	v_cndmask_b32_e32 v197, v81, v197, vcc
	v_sub_f32_e32 v2, v2, v197
	v_exp_f32_e32 v81, v2
	v_sub_f32_e32 v2, v164, v197
	v_exp_f32_e32 v82, v2
	v_sub_f32_e32 v2, v165, v197
	v_cndmask_b32_e64 v94, v83, 1.0, vcc
	v_exp_f32_e32 v83, v2
	v_sub_f32_e32 v2, v166, v197
	v_exp_f32_e32 v95, v2
	v_sub_f32_e32 v96, v167, v197
	v_add_f32_e32 v2, 0, v81
	v_exp_f32_e32 v96, v96
	v_sub_f32_e32 v97, v168, v197
	v_add_f32_e32 v2, v82, v2
	v_exp_f32_e32 v97, v97
	v_sub_f32_e32 v98, v169, v197
	v_add_f32_e32 v2, v83, v2
	v_exp_f32_e32 v98, v98
	v_sub_f32_e32 v99, v170, v197
	v_add_f32_e32 v2, v95, v2
	v_exp_f32_e32 v99, v99
	v_sub_f32_e32 v164, v171, v197
	v_add_f32_e32 v2, v96, v2
	v_exp_f32_e32 v164, v164
	v_sub_f32_e32 v92, v92, v197
	v_add_f32_e32 v2, v97, v2
	v_exp_f32_e32 v92, v92
	v_sub_f32_e32 v93, v93, v197
	v_add_f32_e32 v2, v98, v2
	v_exp_f32_e32 v93, v93
	v_sub_f32_e32 v76, v76, v197
	v_add_f32_e32 v2, v99, v2
	v_exp_f32_e32 v76, v76
	v_sub_f32_e32 v77, v77, v197
	v_add_f32_e32 v2, v164, v2
	v_exp_f32_e32 v77, v77
	v_sub_f32_e32 v78, v78, v197
	v_add_f32_e32 v2, v92, v2
	v_exp_f32_e32 v78, v78
	v_sub_f32_e32 v79, v79, v197
	v_add_f32_e32 v2, v93, v2
	v_exp_f32_e32 v79, v79
	v_sub_f32_e32 v80, v80, v197
	v_add_f32_e32 v2, v76, v2
	v_exp_f32_e32 v80, v80
	v_sub_f32_e32 v90, v90, v197
	v_add_f32_e32 v2, v77, v2
	v_exp_f32_e32 v90, v90
	v_sub_f32_e32 v91, v91, v197
	v_add_f32_e32 v2, v78, v2
	v_exp_f32_e32 v91, v91
	v_sub_f32_e32 v88, v88, v197
	v_add_f32_e32 v2, v79, v2
	v_exp_f32_e32 v88, v88
	v_sub_f32_e32 v89, v89, v197
	v_add_f32_e32 v2, v80, v2
	v_exp_f32_e32 v89, v89
	v_sub_f32_e32 v86, v86, v197
	v_add_f32_e32 v2, v90, v2
	v_exp_f32_e32 v86, v86
	v_sub_f32_e32 v87, v87, v197
	v_add_f32_e32 v2, v91, v2
	v_exp_f32_e32 v87, v87
	v_sub_f32_e32 v84, v84, v197
	v_add_f32_e32 v2, v88, v2
	v_exp_f32_e32 v165, v84
	v_sub_f32_e32 v84, v85, v197
	v_add_f32_e32 v2, v89, v2
	v_exp_f32_e32 v85, v84
	v_sub_f32_e32 v70, v70, v197
	v_add_f32_e32 v2, v86, v2
	v_exp_f32_e32 v166, v70
	v_sub_f32_e32 v70, v71, v197
	v_add_f32_e32 v2, v87, v2
	v_exp_f32_e32 v167, v70
	v_sub_f32_e32 v70, v72, v197
	v_add_f32_e32 v2, v165, v2
	v_exp_f32_e32 v168, v70
	v_sub_f32_e32 v70, v73, v197
	v_add_f32_e32 v2, v85, v2
	v_exp_f32_e32 v169, v70
	v_sub_f32_e32 v68, v68, v197
	v_add_f32_e32 v2, v166, v2
	v_exp_f32_e32 v170, v68
	v_sub_f32_e32 v68, v69, v197
	v_add_f32_e32 v2, v167, v2
	v_exp_f32_e32 v171, v68
	v_sub_f32_e32 v68, v74, v197
	v_add_f32_e32 v2, v168, v2
	v_exp_f32_e32 v199, v68
	v_sub_f32_e32 v68, v75, v197
	v_add_f32_e32 v2, v169, v2
	v_exp_f32_e32 v200, v68
	v_add_f32_e32 v2, v170, v2
	v_add_f32_e32 v2, v171, v2
	v_add_f32_e32 v2, v199, v2
	v_add_f32_e32 v2, v200, v2
	v_mov_b32_e32 v84, v2
	v_cvt_pk_bf16_f32 v68, v81, v82
	v_cvt_pk_bf16_f32 v69, v83, v95
	v_cvt_pk_bf16_f32 v70, v96, v97
	v_cvt_pk_bf16_f32 v71, v98, v99
	v_cvt_pk_bf16_f32 v72, v164, v92
	v_cvt_pk_bf16_f32 v73, v93, v76
	v_cvt_pk_bf16_f32 v74, v77, v78
	v_cvt_pk_bf16_f32 v75, v79, v80
	v_cvt_pk_bf16_f32 v80, v90, v91
	v_cvt_pk_bf16_f32 v81, v88, v89
	v_cvt_pk_bf16_f32 v82, v86, v87
	v_cvt_pk_bf16_f32 v83, v165, v85
	v_cvt_pk_bf16_f32 v76, v166, v167
	v_cvt_pk_bf16_f32 v77, v168, v169
	v_cvt_pk_bf16_f32 v78, v170, v171
	v_cvt_pk_bf16_f32 v79, v199, v200
	s_nop 1
	v_permlane32_swap_b32_e32 v2, v84
	v_permlane32_swap_b32_e32 v68, v70
	v_permlane32_swap_b32_e32 v69, v71
	v_permlane32_swap_b32_e32 v72, v74
	v_permlane32_swap_b32_e32 v73, v75
	v_permlane32_swap_b32_e32 v80, v82
	v_permlane32_swap_b32_e32 v81, v83
	v_permlane32_swap_b32_e32 v76, v78
	v_permlane32_swap_b32_e32 v77, v79
	v_add_f32_e32 v2, v2, v84
	v_fmac_f32_e32 v2, v198, v94
	s_cmp_eq_u32 s100, 0
	s_cbranch_scc0 .Lmy_defer_s3
	s_mov_b32 s98, s91

; #define RESC(a) do { if (__any((a) < 1.f)) { if (hi == 0) al_l[r32] = (a); asm volatile("s_waitcnt lgkmcnt(0)" ::: "memory"); \
;     _Pragma("unroll") for (int d = 0; d < 4; ++d) _Pragma("unroll") for (int r = 0; r < 16; ++r) o[d][r] *= al_l[crow(r, hi)]; asm volatile("s_waitcnt lgkmcnt(0)" ::: "memory"); } } while (0)
; template <int VAR>
; __device__ __forceinline__ void nsa_attn_mfma(Frame& F, bf16* Y) {
;     ...
;           float alpha_; bf16x8 pa0_, pa1_, pa2_, pa3_; TILE_SM(kb, pa0_, pa1_, pa2_, pa3_, alpha_); RESC(alpha_);
;           if (VAR != 2) pv_d0(o, vb0 + vbuf * SHM_V, pa0_, pa1_, pa2_, pa3_); else { o[0][0] += __builtin_bit_cast(float, pa0_[0] | (pa1_[1] << 16)) + __builtin_bit_cast(float, pa2_[0] | (pa3_[1] << 16)); } }
;         if (kbn < 0) break;
;         kb = kbn; ++it; vbuf = vbn;
;       }
.Lmy_tail_s3:
	s_add_i32 s4, s81, 1
	s_andn2_b64 vcc, exec, s[84:85]
	s_cbranch_vccz .Lmy_exit_s3
	s_mov_b32 s81, s4
	v_mov_b32_e32 v198, v2
	s_mov_b32 s7, s82
	s_mov_b32 s91, s87
	s_mov_b32 s6, s77
	s_branch .LBB0_2422

; #define TWAIT() do { asm volatile("s_waitcnt vmcnt(0)" ::: "memory"); __syncthreads(); } while (0)
; template <int VAR>
; __device__ __forceinline__ void nsa_attn_mfma(Frame& F, bf16* Y) {
;     ...
;       if (VAR < 5) for (;;) {
;         const int kbuf = it & 1;
;         TWAIT();
;         const int kbn = tiles ? 31 - __builtin_clz(tiles) : -1; const int vbn = (vbuf == 2) ? 0 : vbuf + 1;
.LBB0_2438:
	s_and_b32 s9, s81, 1
	s_cmp_eq_u32 s7, 0
	s_waitcnt vmcnt(0)
	s_cselect_b64 s[10:11], -1, 0
	s_add_i32 s4, s87, 1
	s_cmp_lg_u32 s87, 2
	s_cselect_b32 s12, s4, 0
	s_cmp_lg_u32 s7, 0
	s_barrier
	s_cmp_eq_u32 s99, 1
	s_cbranch_scc1 .Lmy_pv_w3

; __device__ __forceinline__ float swapmax(float x) { auto rr = __builtin_amdgcn_permlane32_swap(__float_as_uint(x), __float_as_uint(x), false, false); return fmaxf(__uint_as_float(rr[0]), __uint_as_float(rr[1])); }
; __device__ __forceinline__ float swapsum(float x) { auto rr = __builtin_amdgcn_permlane32_swap(__float_as_uint(x), __float_as_uint(x), false, false); return __uint_as_float(rr[0]) + __uint_as_float(rr[1]); }
; __device__ __forceinline__ void softmax_step(f32x16& p0, f32x16& p1, float& m, float& l, float& alpha, bf16x8& pa0, bf16x8& pa1, bf16x8& pa2, bf16x8& pa3) {
;   float pmax = p0[0];
; #pragma unroll
;   for (int r = 1; r < 16; ++r) pmax = fmaxf(pmax, p0[r]);
; #pragma unroll
;   for (int r = 0; r < 16; ++r) pmax = fmaxf(pmax, p1[r]);
;   pmax = swapmax(pmax);
;   if (__all(pmax - m <= THR2)) { alpha = 1.f; }
;   else { const float mn = fmaxf(m, pmax); alpha = __builtin_amdgcn_exp2f(m - mn); m = mn; }
;   float ps = 0.f;
; #pragma unroll
;   for (int r = 0; r < 16; ++r) { p0[r] = __builtin_amdgcn_exp2f(p0[r] - m); ps += p0[r]; }
; #pragma unroll
;   for (int r = 0; r < 16; ++r) { p1[r] = __builtin_amdgcn_exp2f(p1[r] - m); ps += p1[r]; }
;   ps = swapsum(ps);
;   l = l * alpha + ps;
;   PK4(p0, 0, pa0); PK4(p0, 8, pa1); PK4(p1, 0, pa2); PK4(p1, 8, pa3);
; }
.LBB0_2445:
	v_max_f32_e32 v82, v155, v155
	v_max_f32_e32 v83, v154, v154
	v_max_f32_e32 v82, v83, v82
	v_max3_f32 v82, v82, v86, v87
	v_max3_f32 v82, v82, v88, v89
	v_max3_f32 v82, v82, v90, v91
	v_max3_f32 v82, v82, v92, v93
	v_max3_f32 v82, v82, v94, v95
	v_max3_f32 v82, v82, v96, v97
	v_max3_f32 v82, v82, v80, v81
	v_max3_f32 v82, v82, v84, v85
	v_max3_f32 v82, v82, v158, v76
	v_max3_f32 v82, v82, v77, v72
	v_max3_f32 v82, v82, v73, v78
	v_max3_f32 v82, v82, v79, v74
	v_max3_f32 v82, v82, v75, v68
	v_max3_f32 v82, v82, v69, v70
	v_max3_f32 v82, v82, v71, v2
	v_mov_b32_e32 v83, v82
	s_nop 1
	v_permlane32_swap_b32_e32 v82, v83
	v_max_f32_e32 v83, v83, v83
	v_max_f32_e32 v82, v82, v82
	v_max_f32_e32 v82, v82, v83
	v_sub_f32_e32 v83, v82, v156
	v_cmp_ge_f32_e32 vcc, s72, v83
	v_max_f32_e32 v98, v156, v156
	s_cmp_eq_u64 vcc, exec
	v_max_f32_e32 v82, v98, v82
	s_cselect_b64 vcc, -1, 0
	v_sub_f32_e32 v98, v156, v82
	v_cndmask_b32_e32 v156, v82, v156, vcc
	v_sub_f32_e32 v82, v154, v156
	v_exp_f32_e32 v82, v82
	v_sub_f32_e32 v83, v155, v156
	v_exp_f32_e32 v83, v83
	v_sub_f32_e32 v86, v86, v156
	v_exp_f32_e32 v86, v86
	v_sub_f32_e32 v87, v87, v156
	v_exp_f32_e32 v87, v87
	v_sub_f32_e32 v88, v88, v156
	v_add_f32_e32 v99, 0, v82
	v_exp_f32_e32 v88, v88
	v_sub_f32_e32 v89, v89, v156
	v_add_f32_e32 v99, v83, v99
	v_exp_f32_e32 v89, v89
	v_sub_f32_e32 v90, v90, v156
	v_add_f32_e32 v99, v86, v99
	v_exp_f32_e32 v90, v90
	v_sub_f32_e32 v91, v91, v156
	v_add_f32_e32 v99, v87, v99
	v_exp_f32_e32 v91, v91
	v_sub_f32_e32 v92, v92, v156
	v_add_f32_e32 v99, v88, v99
	v_exp_f32_e32 v92, v92
	v_sub_f32_e32 v93, v93, v156
	v_add_f32_e32 v99, v89, v99
	v_exp_f32_e32 v93, v93
	v_sub_f32_e32 v94, v94, v156
	v_add_f32_e32 v99, v90, v99
	v_exp_f32_e32 v94, v94
	v_sub_f32_e32 v95, v95, v156
	v_add_f32_e32 v99, v91, v99
	v_exp_f32_e32 v95, v95
	v_sub_f32_e32 v96, v96, v156
	v_add_f32_e32 v99, v92, v99
	v_exp_f32_e32 v96, v96
	v_sub_f32_e32 v97, v97, v156
	v_add_f32_e32 v99, v93, v99
	v_exp_f32_e32 v97, v97
	v_sub_f32_e32 v80, v80, v156
	v_add_f32_e32 v99, v94, v99
	v_exp_f32_e32 v80, v80
	v_sub_f32_e32 v81, v81, v156
	v_add_f32_e32 v99, v95, v99
	v_exp_f32_e32 v81, v81
	v_sub_f32_e32 v84, v84, v156
	v_add_f32_e32 v99, v96, v99
	v_exp_f32_e32 v154, v84
	v_sub_f32_e32 v84, v85, v156
	v_add_f32_e32 v99, v97, v99
	v_exp_f32_e32 v85, v84
	v_sub_f32_e32 v84, v158, v156
	v_add_f32_e32 v99, v80, v99
	v_exp_f32_e32 v155, v84
	v_sub_f32_e32 v76, v76, v156
	v_add_f32_e32 v99, v81, v99
	v_exp_f32_e32 v76, v76
	v_sub_f32_e32 v77, v77, v156
	v_add_f32_e32 v84, v154, v99
	v_exp_f32_e32 v77, v77
	v_sub_f32_e32 v72, v72, v156
	v_add_f32_e32 v84, v85, v84
	v_exp_f32_e32 v99, v72
	v_sub_f32_e32 v72, v73, v156
	v_add_f32_e32 v84, v155, v84
	v_exp_f32_e32 v158, v72
	v_sub_f32_e32 v72, v78, v156
	v_add_f32_e32 v84, v76, v84
	v_exp_f32_e32 v78, v72
	v_sub_f32_e32 v73, v79, v156
	v_add_f32_e32 v72, v77, v84
	v_exp_f32_e32 v79, v73
	v_sub_f32_e32 v73, v74, v156
	v_add_f32_e32 v72, v99, v72
	v_exp_f32_e32 v159, v73
	v_sub_f32_e32 v73, v75, v156
	v_add_f32_e32 v72, v158, v72
	v_exp_f32_e32 v160, v73
	v_sub_f32_e32 v68, v68, v156
	v_add_f32_e32 v72, v78, v72
	v_exp_f32_e32 v161, v68
	v_sub_f32_e32 v69, v69, v156
	v_add_f32_e32 v68, v79, v72
	v_exp_f32_e32 v162, v69
	v_sub_f32_e32 v69, v70, v156
	v_add_f32_e32 v68, v159, v68
	v_exp_f32_e32 v163, v69
	v_sub_f32_e32 v69, v71, v156
	v_add_f32_e32 v68, v160, v68
	v_exp_f32_e32 v164, v69
	v_sub_f32_e32 v2, v2, v156
	v_add_f32_e32 v68, v161, v68
	v_exp_f32_e32 v165, v2
	v_exp_f32_e32 v98, v98
	v_add_f32_e32 v2, v162, v68
	v_add_f32_e32 v2, v163, v2
	v_add_f32_e32 v2, v164, v2
	v_add_f32_e32 v2, v165, v2
	v_cndmask_b32_e64 v98, v98, 1.0, vcc
	v_mov_b32_e32 v84, v2
	v_cvt_pk_bf16_f32 v68, v82, v83
	v_cvt_pk_bf16_f32 v69, v86, v87
	v_cvt_pk_bf16_f32 v70, v88, v89
	v_cvt_pk_bf16_f32 v71, v90, v91
	v_cvt_pk_bf16_f32 v72, v92, v93
	v_cvt_pk_bf16_f32 v73, v94, v95
	v_cvt_pk_bf16_f32 v74, v96, v97
	v_cvt_pk_bf16_f32 v75, v80, v81
	v_cvt_pk_bf16_f32 v80, v154, v85
	v_cvt_pk_bf16_f32 v81, v155, v76
	v_cvt_pk_bf16_f32 v82, v77, v99
	v_cvt_pk_bf16_f32 v83, v158, v78
	v_cvt_pk_bf16_f32 v76, v79, v159
	v_cvt_pk_bf16_f32 v77, v160, v161
	v_cvt_pk_bf16_f32 v78, v162, v163
	v_cvt_pk_bf16_f32 v79, v164, v165
	s_nop 1
	v_permlane32_swap_b32_e32 v2, v84
	v_permlane32_swap_b32_e32 v68, v70
	v_permlane32_swap_b32_e32 v69, v71
	v_permlane32_swap_b32_e32 v72, v74
	v_permlane32_swap_b32_e32 v73, v75
	v_permlane32_swap_b32_e32 v80, v82
	v_permlane32_swap_b32_e32 v81, v83
	v_permlane32_swap_b32_e32 v76, v78
	v_permlane32_swap_b32_e32 v77, v79
	v_add_f32_e32 v2, v2, v84
	v_fmac_f32_e32 v2, v157, v98
	s_cmp_eq_u32 s100, 0
	s_cbranch_scc0 .Lmy_defer_w3
	s_mov_b32 s98, s87

; #define RESC(a) do { if (__any((a) < 1.f)) { if (hi == 0) al_l[r32] = (a); asm volatile("s_waitcnt lgkmcnt(0)" ::: "memory"); \
;     _Pragma("unroll") for (int d = 0; d < 4; ++d) _Pragma("unroll") for (int r = 0; r < 16; ++r) o[d][r] *= al_l[crow(r, hi)]; asm volatile("s_waitcnt lgkmcnt(0)" ::: "memory"); } } while (0)
; template <int VAR>
; __device__ __forceinline__ void nsa_attn_mfma(Frame& F, bf16* Y) {
;     ...
;           float alpha_; bf16x8 pa0_, pa1_, pa2_, pa3_; TILE_SM(kb, pa0_, pa1_, pa2_, pa3_, alpha_); RESC(alpha_);
;           if (VAR != 2) pv_d0(o, vb0 + vbuf * SHM_V, pa0_, pa1_, pa2_, pa3_); else { o[0][0] += __builtin_bit_cast(float, pa0_[0] | (pa1_[1] << 16)) + __builtin_bit_cast(float, pa2_[0] | (pa3_[1] << 16)); } }
;         if (kbn < 0) break;
;         kb = kbn; ++it; vbuf = vbn;
;       }
.Lmy_defer_w3:
	s_mov_b32 s99, 1
	s_mov_b32 s98, s87
.Lmy_tail_w3:
	s_add_i32 s81, s81, 1
	s_andn2_b64 vcc, exec, s[10:11]
	s_cbranch_vccz .Lmy_exit_w3
	v_mov_b32_e32 v157, v2
	s_mov_b32 s7, s14
	s_mov_b32 s87, s12
	s_mov_b32 s6, s13
	s_branch .LBB0_2438
